# all barriers after the first closed per XCC; cross-XCC hand-overs (modulation values, PROJ/CONCAT vs activation overlay) through three done-counters with an L2 writeback by the closing workgroup
# baseline (speedup 1.0000x reference)
; __device__ __forceinline__ unsigned xb_ld(unsigned* p)              { return __hip_atomic_load(p, __ATOMIC_RELAXED, __HIP_MEMORY_SCOPE_AGENT); }
; __device__ __forceinline__ unsigned xb_add(unsigned* p, unsigned v) { return __hip_atomic_fetch_add(p, v, __ATOMIC_RELAXED, __HIP_MEMORY_SCOPE_AGENT); }
; #define XB_SPIN(cond, bar) do { unsigned _sp = 0; while (cond) { __builtin_amdgcn_s_sleep(1); \
;     if ((++_sp & 255u) == 0u) { if (xb_ld(&(bar)[XB_TMO])) break; if (_sp > XB_SPIN_CAP) { atomicAdd(&(bar)[XB_TMO], 1u); break; } } } } while (0)
; __device__ __forceinline__ void xcd_barrier(const XcdBarrier& b) {
;     asm volatile("s_waitcnt vmcnt(0)" ::: "memory");
;     __syncthreads();
;     if (threadIdx.x == 0) {
;         unsigned* bar = b.bar;
;         __builtin_amdgcn_s_waitcnt(0);
;         unsigned nloc = b.st[0], nx = b.st[1];
;         if (nloc == 0u) { xcd_barrier_complete(bar, b.x, nloc, nx); b.st[0] = nloc; b.st[1] = nx; }
;         const unsigned old = xb_add(&bar[XB_XSUB(b.x)], 1u);
;         const unsigned gen = old / nloc;
;         if (old + 1u == (gen + 1u) * nloc) {
;             __builtin_amdgcn_fence(__ATOMIC_RELEASE, "agent");
;             asm volatile("s_waitcnt vmcnt(0)" ::: "memory");
;             const unsigned og = xb_add(&bar[XB_TOP], 1u);
;             const unsigned tg = og / nx;
;             if (og + 1u == (tg + 1u) * nx) xb_add(&bar[XB_TOPGEN], 1u);
;             else XB_SPIN(xb_ld(&bar[XB_TOPGEN]) == tg, bar);
;             __builtin_amdgcn_fence(__ATOMIC_ACQUIRE, "agent");
;             xb_add(&bar[XB_XGEN(b.x)], 1u);
;             asm volatile("s_waitcnt vmcnt(0)" ::: "memory");
;         } else {
;             XB_SPIN(xb_ld(&bar[XB_XGEN(b.x)]) == gen, bar);
.LBB0_153:
	s_andn2_saveexec_b64 s[4:5], s[8:9]
	s_cbranch_execz .LBB0_173
	v_readfirstlane_b32 s100, v247
	s_nop 3
	s_cmp_eq_u32 s100, 0
	s_cbranch_scc1 .Lxb_global_0
	v_readlane_b32 s100, v245, 18
	v_readlane_b32 s101, v245, 19
	v_mov_b32_e32 v251, 0
	v_mov_b32_e32 v250, 1
	s_nop 4
	global_atomic_add v251, v250, s[100:101]
	buffer_wbl2 sc1
	s_waitcnt vmcnt(0)
	global_atomic_add v251, v250, s[94:95] offset:0
	s_waitcnt vmcnt(1)
	s_branch .LBB0_173

; __device__ __forceinline__ unsigned xb_ld(unsigned* p)              { return __hip_atomic_load(p, __ATOMIC_RELAXED, __HIP_MEMORY_SCOPE_AGENT); }
; __device__ __forceinline__ unsigned xb_add(unsigned* p, unsigned v) { return __hip_atomic_fetch_add(p, v, __ATOMIC_RELAXED, __HIP_MEMORY_SCOPE_AGENT); }
; #define XB_SPIN(cond, bar) do { unsigned _sp = 0; while (cond) { __builtin_amdgcn_s_sleep(1); \
;     if ((++_sp & 255u) == 0u) { if (xb_ld(&(bar)[XB_TMO])) break; if (_sp > XB_SPIN_CAP) { atomicAdd(&(bar)[XB_TMO], 1u); break; } } } } while (0)
; #define SEAM() do { for (int rs_ = 0; rs_ < REP_S; ++rs_) xcd_barrier(bar); } while (0)
; __device__ __forceinline__ void xcd_barrier(const XcdBarrier& b) {
;     asm volatile("s_waitcnt vmcnt(0)" ::: "memory");
;     __syncthreads();
;     if (threadIdx.x == 0) {
;         unsigned* bar = b.bar;
;         __builtin_amdgcn_s_waitcnt(0);
;         unsigned nloc = b.st[0], nx = b.st[1];
;         if (nloc == 0u) { xcd_barrier_complete(bar, b.x, nloc, nx); b.st[0] = nloc; b.st[1] = nx; }
;         const unsigned old = xb_add(&bar[XB_XSUB(b.x)], 1u);
;         const unsigned gen = old / nloc;
;         if (old + 1u == (gen + 1u) * nloc) {
;             __builtin_amdgcn_fence(__ATOMIC_RELEASE, "agent");
;             asm volatile("s_waitcnt vmcnt(0)" ::: "memory");
;             const unsigned og = xb_add(&bar[XB_TOP], 1u);
;             const unsigned tg = og / nx;
;             if (og + 1u == (tg + 1u) * nx) xb_add(&bar[XB_TOPGEN], 1u);
;             else XB_SPIN(xb_ld(&bar[XB_TOPGEN]) == tg, bar);
;             __builtin_amdgcn_fence(__ATOMIC_ACQUIRE, "agent");
;             xb_add(&bar[XB_XGEN(b.x)], 1u);
;             asm volatile("s_waitcnt vmcnt(0)" ::: "memory");
;         } else {
;             XB_SPIN(xb_ld(&bar[XB_XGEN(b.x)]) == gen, bar);
; __global__ void __launch_bounds__(512, 2) fwd_kernel(Args a) {
;     ...
;         SEAM();
;         for (int rep = 0; rep < REP_R; ++rep) rowwise_phase(a, lds, false, true, true, true, 2, XB, MIX, nullptr, XA, H, l, 2, a.g_post_mix + l * DM, l, 3, 4, a.g_pre_ffn + l * DM);
.LBB0_482:
	s_andn2_saveexec_b64 s[16:17], s[36:37]
	s_cbranch_execz .LBB0_502
	v_readfirstlane_b32 s100, v247
	s_nop 3
	s_cmp_eq_u32 s100, 0
	s_cbranch_scc1 .Lxb_global_6
	s_mov_b32 s100, 8
	s_mov_b32 s101, 0x8000
	v_mov_b32_e32 v251, 0
.Lxb_poll_6:
	global_load_dword v250, v251, s[94:95] offset:0 sc1
	s_waitcnt vmcnt(0)
	v_cmp_gt_u32_e32 vcc, s100, v250
	s_cbranch_vccz .Lxb_polled_6
	s_sleep 1
	s_sub_u32 s101, s101, 1
	s_cmp_lg_u32 s101, 0
	s_cbranch_scc1 .Lxb_poll_6
.Lxb_polled_6:
	v_readlane_b32 s100, v245, 18
	v_readlane_b32 s101, v245, 19
	v_mov_b32_e32 v251, 0
	v_mov_b32_e32 v250, 1
	s_nop 4
	global_atomic_add v251, v250, s[100:101]
	buffer_wbl2 sc1
	s_waitcnt vmcnt(0)
	global_atomic_add v251, v250, s[94:95] offset:128
	s_waitcnt vmcnt(1)
	s_branch .LBB0_502

; __device__ __forceinline__ unsigned xb_ld(unsigned* p)              { return __hip_atomic_load(p, __ATOMIC_RELAXED, __HIP_MEMORY_SCOPE_AGENT); }
; __device__ __forceinline__ unsigned xb_add(unsigned* p, unsigned v) { return __hip_atomic_fetch_add(p, v, __ATOMIC_RELAXED, __HIP_MEMORY_SCOPE_AGENT); }
; #define XB_SPIN(cond, bar) do { unsigned _sp = 0; while (cond) { __builtin_amdgcn_s_sleep(1); \
;     if ((++_sp & 255u) == 0u) { if (xb_ld(&(bar)[XB_TMO])) break; if (_sp > XB_SPIN_CAP) { atomicAdd(&(bar)[XB_TMO], 1u); break; } } } } while (0)
; __device__ __forceinline__ void xcd_barrier(const XcdBarrier& b) {
;     asm volatile("s_waitcnt vmcnt(0)" ::: "memory");
;     __syncthreads();
;     if (threadIdx.x == 0) {
;         unsigned* bar = b.bar;
;         __builtin_amdgcn_s_waitcnt(0);
;         unsigned nloc = b.st[0], nx = b.st[1];
;         if (nloc == 0u) { xcd_barrier_complete(bar, b.x, nloc, nx); b.st[0] = nloc; b.st[1] = nx; }
;         const unsigned old = xb_add(&bar[XB_XSUB(b.x)], 1u);
;         const unsigned gen = old / nloc;
;         if (old + 1u == (gen + 1u) * nloc) {
;             __builtin_amdgcn_fence(__ATOMIC_RELEASE, "agent");
;             asm volatile("s_waitcnt vmcnt(0)" ::: "memory");
;             const unsigned og = xb_add(&bar[XB_TOP], 1u);
;             const unsigned tg = og / nx;
;             if (og + 1u == (tg + 1u) * nx) xb_add(&bar[XB_TOPGEN], 1u);
;             else XB_SPIN(xb_ld(&bar[XB_TOPGEN]) == tg, bar);
;             __builtin_amdgcn_fence(__ATOMIC_ACQUIRE, "agent");
;             xb_add(&bar[XB_XGEN(b.x)], 1u);
;             asm volatile("s_waitcnt vmcnt(0)" ::: "memory");
;         } else {
;             XB_SPIN(xb_ld(&bar[XB_XGEN(b.x)]) == gen, bar);
.LBB0_551:
	s_andn2_saveexec_b64 s[16:17], s[36:37]
	s_cbranch_execz .LBB0_571
	v_readfirstlane_b32 s100, v247
	s_nop 3
	s_cmp_eq_u32 s100, 0
	s_cbranch_scc1 .Lxb_global_1
	v_readlane_b32 s101, v244, 21
	s_nop 3
	s_add_i32 s101, s101, 1
	s_lshl_b32 s100, s101, 3
	s_mov_b32 s101, 0x8000
	v_mov_b32_e32 v251, 0
.Lxb_poll_1:
	global_load_dword v250, v251, s[94:95] offset:128 sc1
	s_waitcnt vmcnt(0)
	v_cmp_gt_u32_e32 vcc, s100, v250
	s_cbranch_vccz .Lxb_polled_1
	s_sleep 1
	s_sub_u32 s101, s101, 1
	s_cmp_lg_u32 s101, 0
	s_cbranch_scc1 .Lxb_poll_1

; __device__ __forceinline__ unsigned xb_ld(unsigned* p)              { return __hip_atomic_load(p, __ATOMIC_RELAXED, __HIP_MEMORY_SCOPE_AGENT); }
; __device__ __forceinline__ unsigned xb_add(unsigned* p, unsigned v) { return __hip_atomic_fetch_add(p, v, __ATOMIC_RELAXED, __HIP_MEMORY_SCOPE_AGENT); }
; #define XB_SPIN(cond, bar) do { unsigned _sp = 0; while (cond) { __builtin_amdgcn_s_sleep(1); \
;     if ((++_sp & 255u) == 0u) { if (xb_ld(&(bar)[XB_TMO])) break; if (_sp > XB_SPIN_CAP) { atomicAdd(&(bar)[XB_TMO], 1u); break; } } } } while (0)
; __device__ __forceinline__ void xcd_barrier(const XcdBarrier& b) {
;     asm volatile("s_waitcnt vmcnt(0)" ::: "memory");
;     __syncthreads();
;     if (threadIdx.x == 0) {
;         unsigned* bar = b.bar;
;         __builtin_amdgcn_s_waitcnt(0);
;         unsigned nloc = b.st[0], nx = b.st[1];
;         if (nloc == 0u) { xcd_barrier_complete(bar, b.x, nloc, nx); b.st[0] = nloc; b.st[1] = nx; }
;         const unsigned old = xb_add(&bar[XB_XSUB(b.x)], 1u);
;         const unsigned gen = old / nloc;
;         if (old + 1u == (gen + 1u) * nloc) {
;             __builtin_amdgcn_fence(__ATOMIC_RELEASE, "agent");
;             asm volatile("s_waitcnt vmcnt(0)" ::: "memory");
;             const unsigned og = xb_add(&bar[XB_TOP], 1u);
;             const unsigned tg = og / nx;
;             if (og + 1u == (tg + 1u) * nx) xb_add(&bar[XB_TOPGEN], 1u);
;             else XB_SPIN(xb_ld(&bar[XB_TOPGEN]) == tg, bar);
;             __builtin_amdgcn_fence(__ATOMIC_ACQUIRE, "agent");
;             xb_add(&bar[XB_XGEN(b.x)], 1u);
;             asm volatile("s_waitcnt vmcnt(0)" ::: "memory");
;         } else {
;             XB_SPIN(xb_ld(&bar[XB_XGEN(b.x)]) == gen, bar);
.LBB0_695:
	s_andn2_saveexec_b64 s[16:17], s[36:37]
	s_cbranch_execz .LBB0_715
	v_readfirstlane_b32 s100, v247
	s_nop 3
	s_cmp_eq_u32 s100, 0
	s_cbranch_scc1 .Lxb_global_2
	v_readlane_b32 s100, v245, 18
	v_readlane_b32 s101, v245, 19
	v_mov_b32_e32 v251, 0
	v_mov_b32_e32 v250, 1
	s_nop 4
	global_atomic_add v251, v250, s[100:101]
	buffer_wbl2 sc1
	s_waitcnt vmcnt(0)
	global_atomic_add v251, v250, s[94:95] offset:256
	s_waitcnt vmcnt(1)
	s_branch .LBB0_715

; __device__ __forceinline__ unsigned xb_ld(unsigned* p)              { return __hip_atomic_load(p, __ATOMIC_RELAXED, __HIP_MEMORY_SCOPE_AGENT); }
; __device__ __forceinline__ unsigned xb_add(unsigned* p, unsigned v) { return __hip_atomic_fetch_add(p, v, __ATOMIC_RELAXED, __HIP_MEMORY_SCOPE_AGENT); }
; #define XB_SPIN(cond, bar) do { unsigned _sp = 0; while (cond) { __builtin_amdgcn_s_sleep(1); \
;     if ((++_sp & 255u) == 0u) { if (xb_ld(&(bar)[XB_TMO])) break; if (_sp > XB_SPIN_CAP) { atomicAdd(&(bar)[XB_TMO], 1u); break; } } } } while (0)
; #define SEAM() do { for (int rs_ = 0; rs_ < REP_S; ++rs_) xcd_barrier(bar); } while (0)
; __device__ __forceinline__ void xcd_barrier(const XcdBarrier& b) {
;     asm volatile("s_waitcnt vmcnt(0)" ::: "memory");
;     __syncthreads();
;     if (threadIdx.x == 0) {
;         unsigned* bar = b.bar;
;         __builtin_amdgcn_s_waitcnt(0);
;         unsigned nloc = b.st[0], nx = b.st[1];
;         if (nloc == 0u) { xcd_barrier_complete(bar, b.x, nloc, nx); b.st[0] = nloc; b.st[1] = nx; }
;         const unsigned old = xb_add(&bar[XB_XSUB(b.x)], 1u);
;         const unsigned gen = old / nloc;
;         if (old + 1u == (gen + 1u) * nloc) {
;             __builtin_amdgcn_fence(__ATOMIC_RELEASE, "agent");
;             asm volatile("s_waitcnt vmcnt(0)" ::: "memory");
;             const unsigned og = xb_add(&bar[XB_TOP], 1u);
;             const unsigned tg = og / nx;
;             if (og + 1u == (tg + 1u) * nx) xb_add(&bar[XB_TOPGEN], 1u);
;             else XB_SPIN(xb_ld(&bar[XB_TOPGEN]) == tg, bar);
;             __builtin_amdgcn_fence(__ATOMIC_ACQUIRE, "agent");
;             xb_add(&bar[XB_XGEN(b.x)], 1u);
;             asm volatile("s_waitcnt vmcnt(0)" ::: "memory");
;         } else {
;             XB_SPIN(xb_ld(&bar[XB_XGEN(b.x)]) == gen, bar);
; __global__ void __launch_bounds__(512, 2) fwd_kernel(Args a) {
;     ...
;         if (more) SEAM();
.LBB0_766:
	s_andn2_saveexec_b64 s[16:17], s[18:19]
	s_cbranch_execz .LBB0_175
	v_readfirstlane_b32 s100, v247
	s_nop 3
	s_cmp_eq_u32 s100, 0
	s_cbranch_scc1 .Lxb_global_7
	v_readlane_b32 s101, v244, 21
	s_nop 3
	s_add_i32 s101, s101, 1
	s_lshl_b32 s100, s101, 3
	s_mov_b32 s101, 0x8000
	v_mov_b32_e32 v251, 0
.Lxb_poll_7:
	global_load_dword v250, v251, s[94:95] offset:256 sc1
	s_waitcnt vmcnt(0)
	v_cmp_gt_u32_e32 vcc, s100, v250
	s_cbranch_vccz .Lxb_polled_7
	s_sleep 1
	s_sub_u32 s101, s101, 1
	s_cmp_lg_u32 s101, 0
	s_cbranch_scc1 .Lxb_poll_7

; __device__ __forceinline__ unsigned xb_add(unsigned* p, unsigned v) { return __hip_atomic_fetch_add(p, v, __ATOMIC_RELAXED, __HIP_MEMORY_SCOPE_AGENT); }
; __device__ __forceinline__ void xcd_barrier(const XcdBarrier& b) {
;     ...
;     if (threadIdx.x == 0) {
;         unsigned* bar = b.bar;
;         __builtin_amdgcn_s_waitcnt(0);
;         unsigned nloc = b.st[0], nx = b.st[1];
;         if (nloc == 0u) { xcd_barrier_complete(bar, b.x, nloc, nx); b.st[0] = nloc; b.st[1] = nx; }
;         const unsigned old = xb_add(&bar[XB_XSUB(b.x)], 1u);
;         const unsigned gen = old / nloc;
;         if (old + 1u == (gen + 1u) * nloc) {
.Lxb_global_7:
	s_mov_b64 s[16:17], exec
	buffer_wbl2 sc1
	s_waitcnt lgkmcnt(0)
	s_waitcnt vmcnt(0)
	v_mbcnt_lo_u32_b32 v0, s16, 0
	v_mbcnt_hi_u32_b32 v0, s17, v0
	v_cmp_eq_u32_e32 vcc, 0, v0
	s_and_saveexec_b64 s[18:19], vcc
	s_cbranch_execz .LBB0_769
	s_bcnt1_i32_b64 s16, s[16:17]
	v_mov_b32_e32 v3, s16
	v_readlane_b32 s16, v245, 20
	v_readlane_b32 s17, v245, 21
	s_nop 4
	global_atomic_add v3, v1, v3, s[16:17] sc0
